# v40 + P0 pool_w*scale copy loop unrolled (16 loads in flight instead of 8 serialized steps) + GEMV remainder rows loaded together
# speedup vs baseline: 1.0105x; 1.0042x over previous
; __global__ void __launch_bounds__(NWAVES * 64, 2) fwd_kernel(Args args) {
;     ...
;                     const float* wp = w_ada + (size_t)g * 96 + cg * 4;
; #pragma unroll 8
;                     for (int k = kg; k < D; k += 21) { const f32x4 w = *(const f32x4*)(wp + (size_t)k * NMOD); const float c0 = cact[k], c1 = cact[D + k]; a0 += w * c0; a1 += w * c1; }
.LBB0_22:
	s_mov_b64 s[0:1], 0x1f8000
	v_lshl_add_u64 v[92:93], v[16:17], 0, s[0:1]
	v_lshl_add_u64 v[94:95], v[92:93], 0, s[0:1]
	v_lshl_add_u64 v[96:97], v[94:95], 0, s[0:1]
	global_load_dwordx4 v[28:31], v[16:17], off
	global_load_dwordx4 v[100:103], v[92:93], off
	global_load_dwordx4 v[104:107], v[94:95], off
	global_load_dwordx4 v[108:111], v[96:97], off
	v_add_u32_e32 v112, 0x54, v19
	v_add_u32_e32 v113, 0xa8, v19
	v_add_u32_e32 v114, 0xfc, v19
	ds_read2st64_b32 v[32:33], v19 offset1:64
	ds_read2st64_b32 v[116:117], v112 offset1:64
	ds_read2st64_b32 v[118:119], v113 offset1:64
	ds_read2st64_b32 v[120:121], v114 offset1:64
	v_cmp_lt_u32_e64 s[0:1], 1, v3
	s_waitcnt lgkmcnt(0)
	s_nop 1
	v_cndmask_b32_e64 v116, 0, v116, s[0:1]
	v_cndmask_b32_e64 v117, 0, v117, s[0:1]
	v_cmp_lt_u32_e64 s[0:1], 2, v3
	s_nop 2
	v_cndmask_b32_e64 v118, 0, v118, s[0:1]
	v_cndmask_b32_e64 v119, 0, v119, s[0:1]
	v_cmp_lt_u32_e64 s[0:1], 3, v3
	s_nop 2
	v_cndmask_b32_e64 v120, 0, v120, s[0:1]
	v_cndmask_b32_e64 v121, 0, v121, s[0:1]
	v_mad_u32_u24 v18, v3, 21, v18
	v_mov_b32_e32 v34, v33
	v_mov_b32_e32 v122, v117
	v_mov_b32_e32 v124, v119
	v_mov_b32_e32 v126, v121
	s_waitcnt vmcnt(3)
	v_pk_fma_f32 v[6:7], v[30:31], v[32:33], v[6:7] op_sel_hi:[1,0,1]
	v_pk_fma_f32 v[4:5], v[28:29], v[32:33], v[4:5] op_sel_hi:[1,0,1]
	v_pk_fma_f32 v[10:11], v[30:31], v[34:35], v[10:11] op_sel_hi:[1,0,1]
	v_pk_fma_f32 v[8:9], v[28:29], v[34:35], v[8:9] op_sel_hi:[1,0,1]
	s_waitcnt vmcnt(2)
	v_pk_fma_f32 v[6:7], v[102:103], v[116:117], v[6:7] op_sel_hi:[1,0,1]
	v_pk_fma_f32 v[4:5], v[100:101], v[116:117], v[4:5] op_sel_hi:[1,0,1]
	v_pk_fma_f32 v[10:11], v[102:103], v[122:123], v[10:11] op_sel_hi:[1,0,1]
	v_pk_fma_f32 v[8:9], v[100:101], v[122:123], v[8:9] op_sel_hi:[1,0,1]
	s_waitcnt vmcnt(1)
	v_pk_fma_f32 v[6:7], v[106:107], v[118:119], v[6:7] op_sel_hi:[1,0,1]
	v_pk_fma_f32 v[4:5], v[104:105], v[118:119], v[4:5] op_sel_hi:[1,0,1]
	v_pk_fma_f32 v[10:11], v[106:107], v[124:125], v[10:11] op_sel_hi:[1,0,1]
	v_pk_fma_f32 v[8:9], v[104:105], v[124:125], v[8:9] op_sel_hi:[1,0,1]
	s_waitcnt vmcnt(0)
	v_pk_fma_f32 v[6:7], v[110:111], v[120:121], v[6:7] op_sel_hi:[1,0,1]
	v_pk_fma_f32 v[4:5], v[108:109], v[120:121], v[4:5] op_sel_hi:[1,0,1]
	v_pk_fma_f32 v[10:11], v[110:111], v[126:127], v[10:11] op_sel_hi:[1,0,1]
	v_pk_fma_f32 v[8:9], v[108:109], v[126:127], v[8:9] op_sel_hi:[1,0,1]
	s_or_b64 exec, exec, s[96:97]
	v_lshlrev_b32_e32 v19, 2, v18

; __global__ void __launch_bounds__(NWAVES * 64, 2) fwd_kernel(Args args) {
;     ...
;             for (int e = (bx * NWAVES * 64 + tid) * 4; e < PGRP * PGD * PGD; e += G * NWAVES * 64 * 4) {
;                 const int j = e % PGD, gi = e / (PGD * PGD); const f32x4 w = *(const f32x4*)(pool_w + e), sc = *(const f32x4*)(pool_scale + gi * PGD + j);
.LBB0_50:
	v_ashrrev_i32_e32 v1, 31, v2
	v_lshrrev_b32_e32 v3, 22, v1
	v_lshrrev_b32_e32 v1, 12, v1
	v_add_u32_e32 v1, v2, v1
	v_add_u32_e32 v3, v2, v3
	v_ashrrev_i32_e32 v1, 20, v1
	v_and_b32_e32 v3, 0xfffffc00, v3
	v_lshlrev_b32_e32 v194, 10, v1
	v_sub_u32_e32 v192, v2, v3
	v_ashrrev_i32_e32 v195, 31, v194
	v_ashrrev_i32_e32 v193, 31, v192
	v_lshl_add_u64 v[194:195], v[194:195], 2, s[66:67]
	v_lshl_add_u64 v[192:193], v[192:193], 2, v[194:195]
	global_load_dwordx4 v[120:123], v[4:5], off
	v_add_u32_e32 v2, s2, v2
	global_load_dwordx4 v[152:155], v[192:193], off
	v_lshl_add_u64 v[4:5], v[4:5], 0, s[4:5]
	v_ashrrev_i32_e32 v1, 31, v2
	v_lshrrev_b32_e32 v3, 22, v1
	v_lshrrev_b32_e32 v1, 12, v1
	v_add_u32_e32 v1, v2, v1
	v_add_u32_e32 v3, v2, v3
	v_ashrrev_i32_e32 v1, 20, v1
	v_and_b32_e32 v3, 0xfffffc00, v3
	v_lshlrev_b32_e32 v194, 10, v1
	v_sub_u32_e32 v192, v2, v3
	v_ashrrev_i32_e32 v195, 31, v194
	v_ashrrev_i32_e32 v193, 31, v192
	v_lshl_add_u64 v[194:195], v[194:195], 2, s[66:67]
	v_lshl_add_u64 v[192:193], v[192:193], 2, v[194:195]
	global_load_dwordx4 v[124:127], v[4:5], off
	v_add_u32_e32 v2, s2, v2
	global_load_dwordx4 v[156:159], v[192:193], off
	v_lshl_add_u64 v[4:5], v[4:5], 0, s[4:5]
	v_ashrrev_i32_e32 v1, 31, v2
	v_lshrrev_b32_e32 v3, 22, v1
	v_lshrrev_b32_e32 v1, 12, v1
	v_add_u32_e32 v1, v2, v1
	v_add_u32_e32 v3, v2, v3
	v_ashrrev_i32_e32 v1, 20, v1
	v_and_b32_e32 v3, 0xfffffc00, v3
	v_lshlrev_b32_e32 v194, 10, v1
	v_sub_u32_e32 v192, v2, v3
	v_ashrrev_i32_e32 v195, 31, v194
	v_ashrrev_i32_e32 v193, 31, v192
	v_lshl_add_u64 v[194:195], v[194:195], 2, s[66:67]
	v_lshl_add_u64 v[192:193], v[192:193], 2, v[194:195]
	global_load_dwordx4 v[128:131], v[4:5], off
	v_add_u32_e32 v2, s2, v2
	global_load_dwordx4 v[160:163], v[192:193], off
	v_lshl_add_u64 v[4:5], v[4:5], 0, s[4:5]
	v_ashrrev_i32_e32 v1, 31, v2
	v_lshrrev_b32_e32 v3, 22, v1
	v_lshrrev_b32_e32 v1, 12, v1
	v_add_u32_e32 v1, v2, v1
	v_add_u32_e32 v3, v2, v3
	v_ashrrev_i32_e32 v1, 20, v1
	v_and_b32_e32 v3, 0xfffffc00, v3
	v_lshlrev_b32_e32 v194, 10, v1
	v_sub_u32_e32 v192, v2, v3
	v_ashrrev_i32_e32 v195, 31, v194
	v_ashrrev_i32_e32 v193, 31, v192
	v_lshl_add_u64 v[194:195], v[194:195], 2, s[66:67]
	v_lshl_add_u64 v[192:193], v[192:193], 2, v[194:195]
	global_load_dwordx4 v[132:135], v[4:5], off
	v_add_u32_e32 v2, s2, v2
	global_load_dwordx4 v[164:167], v[192:193], off
	v_lshl_add_u64 v[4:5], v[4:5], 0, s[4:5]
	v_ashrrev_i32_e32 v1, 31, v2
	v_lshrrev_b32_e32 v3, 22, v1
	v_lshrrev_b32_e32 v1, 12, v1
	v_add_u32_e32 v1, v2, v1
	v_add_u32_e32 v3, v2, v3
	v_ashrrev_i32_e32 v1, 20, v1
	v_and_b32_e32 v3, 0xfffffc00, v3
	v_lshlrev_b32_e32 v194, 10, v1
	v_sub_u32_e32 v192, v2, v3
	v_ashrrev_i32_e32 v195, 31, v194
	v_ashrrev_i32_e32 v193, 31, v192
	v_lshl_add_u64 v[194:195], v[194:195], 2, s[66:67]
	v_lshl_add_u64 v[192:193], v[192:193], 2, v[194:195]
	global_load_dwordx4 v[136:139], v[4:5], off
	v_add_u32_e32 v2, s2, v2
	global_load_dwordx4 v[168:171], v[192:193], off
	v_lshl_add_u64 v[4:5], v[4:5], 0, s[4:5]
	v_ashrrev_i32_e32 v1, 31, v2
	v_lshrrev_b32_e32 v3, 22, v1
	v_lshrrev_b32_e32 v1, 12, v1
	v_add_u32_e32 v1, v2, v1
	v_add_u32_e32 v3, v2, v3
	v_ashrrev_i32_e32 v1, 20, v1
	v_and_b32_e32 v3, 0xfffffc00, v3
	v_lshlrev_b32_e32 v194, 10, v1
	v_sub_u32_e32 v192, v2, v3
	v_ashrrev_i32_e32 v195, 31, v194
	v_ashrrev_i32_e32 v193, 31, v192
	v_lshl_add_u64 v[194:195], v[194:195], 2, s[66:67]
	v_lshl_add_u64 v[192:193], v[192:193], 2, v[194:195]
	global_load_dwordx4 v[140:143], v[4:5], off
	v_add_u32_e32 v2, s2, v2
	global_load_dwordx4 v[172:175], v[192:193], off
	v_lshl_add_u64 v[4:5], v[4:5], 0, s[4:5]
	v_ashrrev_i32_e32 v1, 31, v2
	v_lshrrev_b32_e32 v3, 22, v1
	v_lshrrev_b32_e32 v1, 12, v1
	v_add_u32_e32 v1, v2, v1
	v_add_u32_e32 v3, v2, v3
	v_ashrrev_i32_e32 v1, 20, v1
	v_and_b32_e32 v3, 0xfffffc00, v3
	v_lshlrev_b32_e32 v194, 10, v1
	v_sub_u32_e32 v192, v2, v3
	v_ashrrev_i32_e32 v195, 31, v194
	v_ashrrev_i32_e32 v193, 31, v192
	v_lshl_add_u64 v[194:195], v[194:195], 2, s[66:67]
	v_lshl_add_u64 v[192:193], v[192:193], 2, v[194:195]
	global_load_dwordx4 v[144:147], v[4:5], off
	v_add_u32_e32 v2, s2, v2
	global_load_dwordx4 v[184:187], v[192:193], off
	v_lshl_add_u64 v[4:5], v[4:5], 0, s[4:5]
	v_ashrrev_i32_e32 v1, 31, v2
	v_lshrrev_b32_e32 v3, 22, v1
	v_lshrrev_b32_e32 v1, 12, v1
	v_add_u32_e32 v1, v2, v1
	v_add_u32_e32 v3, v2, v3
	v_ashrrev_i32_e32 v1, 20, v1
	v_and_b32_e32 v3, 0xfffffc00, v3
	v_lshlrev_b32_e32 v194, 10, v1
	v_sub_u32_e32 v192, v2, v3
	v_ashrrev_i32_e32 v195, 31, v194
	v_ashrrev_i32_e32 v193, 31, v192
	v_lshl_add_u64 v[194:195], v[194:195], 2, s[66:67]
	v_lshl_add_u64 v[192:193], v[192:193], 2, v[194:195]
	global_load_dwordx4 v[148:151], v[4:5], off
	v_add_u32_e32 v2, s2, v2
	global_load_dwordx4 v[188:191], v[192:193], off
	v_lshl_add_u64 v[4:5], v[4:5], 0, s[4:5]
	s_waitcnt vmcnt(0)
; __device__ __forceinline__ unsigned cvt_pk_bf16(float lo, float hi) { unsigned r; asm volatile("v_cvt_pk_bf16_f32 %0, %1, %2" : "=v"(r) : "v"(lo), "v"(hi)); return r; }
; __global__ void __launch_bounds__(NWAVES * 64, 2) fwd_kernel(Args args) {
;     ...
;                 const int j = e % PGD, gi = e / (PGD * PGD); const f32x4 w = *(const f32x4*)(pool_w + e), sc = *(const f32x4*)(pool_scale + gi * PGD + j);
;                 v2u o; o.x = cvt_pk_bf16(w.x * sc.x, w.y * sc.y); o.y = cvt_pk_bf16(w.z * sc.z, w.w * sc.w); *(v2u*)(Wpool_t + e) = o; }
	v_mul_f32_e32 v196, v120, v152
	v_mul_f32_e32 v197, v121, v153
	v_mul_f32_e32 v198, v122, v154
	v_mul_f32_e32 v199, v123, v155
	v_cvt_pk_bf16_f32 v200, v196, v197
	v_cvt_pk_bf16_f32 v201, v198, v199
	global_store_dwordx2 v[6:7], v[200:201], off
	v_lshl_add_u64 v[6:7], v[6:7], 0, s[38:39]
	s_nop 1
	v_mul_f32_e32 v196, v124, v156
	v_mul_f32_e32 v197, v125, v157
	v_mul_f32_e32 v198, v126, v158
	v_mul_f32_e32 v199, v127, v159
	v_cvt_pk_bf16_f32 v200, v196, v197
	v_cvt_pk_bf16_f32 v201, v198, v199
	global_store_dwordx2 v[6:7], v[200:201], off
	v_lshl_add_u64 v[6:7], v[6:7], 0, s[38:39]
	s_nop 1
	v_mul_f32_e32 v196, v128, v160
	v_mul_f32_e32 v197, v129, v161
	v_mul_f32_e32 v198, v130, v162
	v_mul_f32_e32 v199, v131, v163
	v_cvt_pk_bf16_f32 v200, v196, v197
	v_cvt_pk_bf16_f32 v201, v198, v199
	global_store_dwordx2 v[6:7], v[200:201], off
	v_lshl_add_u64 v[6:7], v[6:7], 0, s[38:39]
	s_nop 1
	v_mul_f32_e32 v196, v132, v164
	v_mul_f32_e32 v197, v133, v165
	v_mul_f32_e32 v198, v134, v166
	v_mul_f32_e32 v199, v135, v167
	v_cvt_pk_bf16_f32 v200, v196, v197
	v_cvt_pk_bf16_f32 v201, v198, v199
	global_store_dwordx2 v[6:7], v[200:201], off
	v_lshl_add_u64 v[6:7], v[6:7], 0, s[38:39]
	s_nop 1
	v_mul_f32_e32 v196, v136, v168
	v_mul_f32_e32 v197, v137, v169
	v_mul_f32_e32 v198, v138, v170
	v_mul_f32_e32 v199, v139, v171
	v_cvt_pk_bf16_f32 v200, v196, v197
	v_cvt_pk_bf16_f32 v201, v198, v199
	global_store_dwordx2 v[6:7], v[200:201], off
	v_lshl_add_u64 v[6:7], v[6:7], 0, s[38:39]
	s_nop 1
	v_mul_f32_e32 v196, v140, v172
	v_mul_f32_e32 v197, v141, v173
	v_mul_f32_e32 v198, v142, v174
	v_mul_f32_e32 v199, v143, v175
	v_cvt_pk_bf16_f32 v200, v196, v197
	v_cvt_pk_bf16_f32 v201, v198, v199
	global_store_dwordx2 v[6:7], v[200:201], off
	v_lshl_add_u64 v[6:7], v[6:7], 0, s[38:39]
	s_nop 1
	v_mul_f32_e32 v196, v144, v184
	v_mul_f32_e32 v197, v145, v185
	v_mul_f32_e32 v198, v146, v186
	v_mul_f32_e32 v199, v147, v187
	v_cvt_pk_bf16_f32 v200, v196, v197
	v_cvt_pk_bf16_f32 v201, v198, v199
	global_store_dwordx2 v[6:7], v[200:201], off
	v_lshl_add_u64 v[6:7], v[6:7], 0, s[38:39]
	s_nop 1
	v_mul_f32_e32 v196, v148, v188
	v_mul_f32_e32 v197, v149, v189
	v_mul_f32_e32 v198, v150, v190
	v_mul_f32_e32 v199, v151, v191
	v_cvt_pk_bf16_f32 v200, v196, v197
	v_cvt_pk_bf16_f32 v201, v198, v199
	global_store_dwordx2 v[6:7], v[200:201], off
	v_lshl_add_u64 v[6:7], v[6:7], 0, s[38:39]
	s_nop 1
